# m3 tile loads unrolled with 8 loads in flight; r2 carry-chain loads batched (clamped addresses) before the fma chain
# speedup vs baseline: 1.0662x; 1.0110x over previous
.LBB0_864:
	global_load_dwordx2 v[100:101], v[2:3], off
	s_cmp_gt_u32 s0, 1
	s_cselect_b64 s[100:101], s[8:9], 0
	v_lshl_add_u64 v[2:3], v[2:3], 0, s[100:101]
	global_load_dwordx2 v[102:103], v[2:3], off
	s_cmp_gt_u32 s0, 2
	s_cselect_b64 s[100:101], s[8:9], 0
	v_lshl_add_u64 v[2:3], v[2:3], 0, s[100:101]
	global_load_dwordx2 v[104:105], v[2:3], off
	s_cmp_gt_u32 s0, 3
	s_cselect_b64 s[100:101], s[8:9], 0
	v_lshl_add_u64 v[2:3], v[2:3], 0, s[100:101]
	global_load_dwordx2 v[106:107], v[2:3], off
	s_cmp_gt_u32 s0, 4
	s_cselect_b64 s[100:101], s[8:9], 0
	v_lshl_add_u64 v[2:3], v[2:3], 0, s[100:101]
	global_load_dwordx2 v[108:109], v[2:3], off
	s_cmp_gt_u32 s0, 5
	s_cselect_b64 s[100:101], s[8:9], 0
	v_lshl_add_u64 v[2:3], v[2:3], 0, s[100:101]
	global_load_dwordx2 v[110:111], v[2:3], off
	s_cmp_gt_u32 s0, 6
	s_cselect_b64 s[100:101], s[8:9], 0
	v_lshl_add_u64 v[2:3], v[2:3], 0, s[100:101]
	global_load_dwordx2 v[112:113], v[2:3], off
	s_cmp_gt_u32 s0, 7
	s_cselect_b64 s[100:101], s[8:9], 0
	v_lshl_add_u64 v[2:3], v[2:3], 0, s[100:101]
	global_load_dwordx2 v[114:115], v[2:3], off
	s_cmp_gt_u32 s0, 8
	s_cselect_b64 s[100:101], s[8:9], 0
	v_lshl_add_u64 v[2:3], v[2:3], 0, s[100:101]
	global_load_dwordx2 v[116:117], v[2:3], off
	s_cmp_gt_u32 s0, 9
	s_cselect_b64 s[100:101], s[8:9], 0
	v_lshl_add_u64 v[2:3], v[2:3], 0, s[100:101]
	global_load_dwordx2 v[118:119], v[2:3], off
	s_cmp_gt_u32 s0, 10
	s_cselect_b64 s[100:101], s[8:9], 0
	v_lshl_add_u64 v[2:3], v[2:3], 0, s[100:101]
	global_load_dwordx2 v[120:121], v[2:3], off
	s_cmp_gt_u32 s0, 11
	s_cselect_b64 s[100:101], s[8:9], 0
	v_lshl_add_u64 v[2:3], v[2:3], 0, s[100:101]
	global_load_dwordx2 v[122:123], v[2:3], off
	s_cmp_gt_u32 s0, 12
	s_cselect_b64 s[100:101], s[8:9], 0
	v_lshl_add_u64 v[2:3], v[2:3], 0, s[100:101]
	global_load_dwordx2 v[124:125], v[2:3], off
	s_cmp_gt_u32 s0, 13
	s_cselect_b64 s[100:101], s[8:9], 0
	v_lshl_add_u64 v[2:3], v[2:3], 0, s[100:101]
	global_load_dwordx2 v[126:127], v[2:3], off
	s_cmp_gt_u32 s0, 14
	s_cselect_b64 s[100:101], s[8:9], 0
	v_lshl_add_u64 v[2:3], v[2:3], 0, s[100:101]
	global_load_dwordx2 v[128:129], v[2:3], off
	s_waitcnt vmcnt(14)
	v_fma_f32 v1, v1, v100, v101
	s_cmp_eq_u32 s0, 1
	s_cbranch_scc1 .Lr2c_done0
	s_waitcnt vmcnt(13)
	v_fma_f32 v1, v1, v102, v103
	s_cmp_eq_u32 s0, 2
	s_cbranch_scc1 .Lr2c_done0
	s_waitcnt vmcnt(12)
	v_fma_f32 v1, v1, v104, v105
	s_cmp_eq_u32 s0, 3
	s_cbranch_scc1 .Lr2c_done0
	s_waitcnt vmcnt(11)
	v_fma_f32 v1, v1, v106, v107
	s_cmp_eq_u32 s0, 4
	s_cbranch_scc1 .Lr2c_done0
	s_waitcnt vmcnt(10)
	v_fma_f32 v1, v1, v108, v109
	s_cmp_eq_u32 s0, 5
	s_cbranch_scc1 .Lr2c_done0
	s_waitcnt vmcnt(9)
	v_fma_f32 v1, v1, v110, v111
	s_cmp_eq_u32 s0, 6
	s_cbranch_scc1 .Lr2c_done0
	s_waitcnt vmcnt(8)
	v_fma_f32 v1, v1, v112, v113
	s_cmp_eq_u32 s0, 7
	s_cbranch_scc1 .Lr2c_done0
	s_waitcnt vmcnt(7)
	v_fma_f32 v1, v1, v114, v115
	s_cmp_eq_u32 s0, 8
	s_cbranch_scc1 .Lr2c_done0
	s_waitcnt vmcnt(6)
	v_fma_f32 v1, v1, v116, v117
	s_cmp_eq_u32 s0, 9
	s_cbranch_scc1 .Lr2c_done0
	s_waitcnt vmcnt(5)
	v_fma_f32 v1, v1, v118, v119
	s_cmp_eq_u32 s0, 10
	s_cbranch_scc1 .Lr2c_done0
	s_waitcnt vmcnt(4)
	v_fma_f32 v1, v1, v120, v121
	s_cmp_eq_u32 s0, 11
	s_cbranch_scc1 .Lr2c_done0
	s_waitcnt vmcnt(3)
	v_fma_f32 v1, v1, v122, v123
	s_cmp_eq_u32 s0, 12
	s_cbranch_scc1 .Lr2c_done0
	s_waitcnt vmcnt(2)
	v_fma_f32 v1, v1, v124, v125
	s_cmp_eq_u32 s0, 13
	s_cbranch_scc1 .Lr2c_done0
	s_waitcnt vmcnt(1)
	v_fma_f32 v1, v1, v126, v127
	s_cmp_eq_u32 s0, 14
	s_cbranch_scc1 .Lr2c_done0
	s_waitcnt vmcnt(0)
	v_fma_f32 v1, v1, v128, v129
.Lr2c_done0:
	s_waitcnt vmcnt(0)
	s_mov_b32 s0, 0

.LBB0_913:
	s_movk_i32 s2, 0xf000
	s_mov_b32 s3, -1
	global_load_dwordx2 v[144:145], v[4:5], off
	s_cmp_gt_u32 s0, 1
	s_cselect_b64 s[100:101], s[2:3], 0
	v_lshl_add_u64 v[4:5], v[4:5], 0, s[100:101]
	global_load_dwordx2 v[146:147], v[4:5], off
	s_cmp_gt_u32 s0, 2
	s_cselect_b64 s[100:101], s[2:3], 0
	v_lshl_add_u64 v[4:5], v[4:5], 0, s[100:101]
	global_load_dwordx2 v[148:149], v[4:5], off
	s_cmp_gt_u32 s0, 3
	s_cselect_b64 s[100:101], s[2:3], 0
	v_lshl_add_u64 v[4:5], v[4:5], 0, s[100:101]
	global_load_dwordx2 v[150:151], v[4:5], off
	s_cmp_gt_u32 s0, 4
	s_cselect_b64 s[100:101], s[2:3], 0
	v_lshl_add_u64 v[4:5], v[4:5], 0, s[100:101]
	global_load_dwordx2 v[152:153], v[4:5], off
	s_cmp_gt_u32 s0, 5
	s_cselect_b64 s[100:101], s[2:3], 0
	v_lshl_add_u64 v[4:5], v[4:5], 0, s[100:101]
	global_load_dwordx2 v[154:155], v[4:5], off
	s_cmp_gt_u32 s0, 6
	s_cselect_b64 s[100:101], s[2:3], 0
	v_lshl_add_u64 v[4:5], v[4:5], 0, s[100:101]
	global_load_dwordx2 v[156:157], v[4:5], off
	s_cmp_gt_u32 s0, 7
	s_cselect_b64 s[100:101], s[2:3], 0
	v_lshl_add_u64 v[4:5], v[4:5], 0, s[100:101]
	global_load_dwordx2 v[158:159], v[4:5], off
	s_cmp_gt_u32 s0, 8
	s_cselect_b64 s[100:101], s[2:3], 0
	v_lshl_add_u64 v[4:5], v[4:5], 0, s[100:101]
	global_load_dwordx2 v[160:161], v[4:5], off
	s_cmp_gt_u32 s0, 9
	s_cselect_b64 s[100:101], s[2:3], 0
	v_lshl_add_u64 v[4:5], v[4:5], 0, s[100:101]
	global_load_dwordx2 v[170:171], v[4:5], off
	s_cmp_gt_u32 s0, 10
	s_cselect_b64 s[100:101], s[2:3], 0
	v_lshl_add_u64 v[4:5], v[4:5], 0, s[100:101]
	global_load_dwordx2 v[172:173], v[4:5], off
	s_cmp_gt_u32 s0, 11
	s_cselect_b64 s[100:101], s[2:3], 0
	v_lshl_add_u64 v[4:5], v[4:5], 0, s[100:101]
	global_load_dwordx2 v[174:175], v[4:5], off
	s_cmp_gt_u32 s0, 12
	s_cselect_b64 s[100:101], s[2:3], 0
	v_lshl_add_u64 v[4:5], v[4:5], 0, s[100:101]
	global_load_dwordx2 v[176:177], v[4:5], off
	s_cmp_gt_u32 s0, 13
	s_cselect_b64 s[100:101], s[2:3], 0
	v_lshl_add_u64 v[4:5], v[4:5], 0, s[100:101]
	global_load_dwordx2 v[178:179], v[4:5], off
	s_cmp_gt_u32 s0, 14
	s_cselect_b64 s[100:101], s[2:3], 0
	v_lshl_add_u64 v[4:5], v[4:5], 0, s[100:101]
	global_load_dwordx2 v[180:181], v[4:5], off
	s_waitcnt vmcnt(14)
	v_fma_f32 v3, v3, v144, v145
	s_cmp_eq_u32 s0, 1
	s_cbranch_scc1 .Lr2c_done1
	s_waitcnt vmcnt(13)
	v_fma_f32 v3, v3, v146, v147
	s_cmp_eq_u32 s0, 2
	s_cbranch_scc1 .Lr2c_done1
	s_waitcnt vmcnt(12)
	v_fma_f32 v3, v3, v148, v149
	s_cmp_eq_u32 s0, 3
	s_cbranch_scc1 .Lr2c_done1
	s_waitcnt vmcnt(11)
	v_fma_f32 v3, v3, v150, v151
	s_cmp_eq_u32 s0, 4
	s_cbranch_scc1 .Lr2c_done1
	s_waitcnt vmcnt(10)
	v_fma_f32 v3, v3, v152, v153
	s_cmp_eq_u32 s0, 5
	s_cbranch_scc1 .Lr2c_done1
	s_waitcnt vmcnt(9)
	v_fma_f32 v3, v3, v154, v155
	s_cmp_eq_u32 s0, 6
	s_cbranch_scc1 .Lr2c_done1
	s_waitcnt vmcnt(8)
	v_fma_f32 v3, v3, v156, v157
	s_cmp_eq_u32 s0, 7
	s_cbranch_scc1 .Lr2c_done1
	s_waitcnt vmcnt(7)
	v_fma_f32 v3, v3, v158, v159
	s_cmp_eq_u32 s0, 8
	s_cbranch_scc1 .Lr2c_done1
	s_waitcnt vmcnt(6)
	v_fma_f32 v3, v3, v160, v161
	s_cmp_eq_u32 s0, 9
	s_cbranch_scc1 .Lr2c_done1
	s_waitcnt vmcnt(5)
	v_fma_f32 v3, v3, v170, v171
	s_cmp_eq_u32 s0, 10
	s_cbranch_scc1 .Lr2c_done1
	s_waitcnt vmcnt(4)
	v_fma_f32 v3, v3, v172, v173
	s_cmp_eq_u32 s0, 11
	s_cbranch_scc1 .Lr2c_done1
	s_waitcnt vmcnt(3)
	v_fma_f32 v3, v3, v174, v175
	s_cmp_eq_u32 s0, 12
	s_cbranch_scc1 .Lr2c_done1
	s_waitcnt vmcnt(2)
	v_fma_f32 v3, v3, v176, v177
	s_cmp_eq_u32 s0, 13
	s_cbranch_scc1 .Lr2c_done1
	s_waitcnt vmcnt(1)
	v_fma_f32 v3, v3, v178, v179
	s_cmp_eq_u32 s0, 14
	s_cbranch_scc1 .Lr2c_done1
	s_waitcnt vmcnt(0)
	v_fma_f32 v3, v3, v180, v181

.LBB0_925:
	v_ashrrev_i32_e32 v6, 31, v1
	v_lshrrev_b32_e32 v6, 28, v6
	v_add_u32_e32 v8, v1, v6
	v_mov_b64_e32 v[4:5], s[70:71]
	v_ashrrev_i32_e32 v6, 4, v8
	v_mad_i64_i32 v[4:5], s[12:13], v6, s74, v[4:5]
	v_lshlrev_b32_e32 v6, 7, v6
	v_sub_u32_e32 v6, v3, v6
	v_ashrrev_i32_e32 v7, 31, v6
	v_lshl_add_u64 v[4:5], v[6:7], 1, v[4:5]
	global_load_dwordx4 v[16:19], v[4:5], off offset:2048
	v_add_u32_e32 v9, 0x100, v1
	v_cmp_lt_i32_e32 vcc, s77, v1
	v_and_b32_e32 v8, -16, v8
	s_or_b64 s[2:3], vcc, s[2:3]
	v_mov_b32_e32 v1, v9
	v_add_u32_e32 v8, v2, v8
	v_add_u32_e32 v2, 0x1000, v2
	v_add_u32_e32 v3, 0x800, v3
	v_mov_b32_e32 v44, v8
	v_ashrrev_i32_e32 v6, 31, v1
	v_lshrrev_b32_e32 v6, 28, v6
	v_add_u32_e32 v8, v1, v6
	v_mov_b64_e32 v[4:5], s[70:71]
	v_ashrrev_i32_e32 v6, 4, v8
	v_mad_i64_i32 v[4:5], s[12:13], v6, s74, v[4:5]
	v_lshlrev_b32_e32 v6, 7, v6
	v_sub_u32_e32 v6, v3, v6
	v_ashrrev_i32_e32 v7, 31, v6
	v_lshl_add_u64 v[4:5], v[6:7], 1, v[4:5]
	global_load_dwordx4 v[20:23], v[4:5], off offset:2048
	v_add_u32_e32 v9, 0x100, v1
	v_cmp_lt_i32_e32 vcc, s77, v1
	v_and_b32_e32 v8, -16, v8
	s_or_b64 s[2:3], vcc, s[2:3]
	v_mov_b32_e32 v1, v9
	v_add_u32_e32 v8, v2, v8
	v_add_u32_e32 v2, 0x1000, v2
	v_add_u32_e32 v3, 0x800, v3
	v_mov_b32_e32 v45, v8
	v_ashrrev_i32_e32 v6, 31, v1
	v_lshrrev_b32_e32 v6, 28, v6
	v_add_u32_e32 v8, v1, v6
	v_mov_b64_e32 v[4:5], s[70:71]
	v_ashrrev_i32_e32 v6, 4, v8
	v_mad_i64_i32 v[4:5], s[12:13], v6, s74, v[4:5]
	v_lshlrev_b32_e32 v6, 7, v6
	v_sub_u32_e32 v6, v3, v6
	v_ashrrev_i32_e32 v7, 31, v6
	v_lshl_add_u64 v[4:5], v[6:7], 1, v[4:5]
	global_load_dwordx4 v[24:27], v[4:5], off offset:2048
	v_add_u32_e32 v9, 0x100, v1
	v_cmp_lt_i32_e32 vcc, s77, v1
	v_and_b32_e32 v8, -16, v8
	s_or_b64 s[2:3], vcc, s[2:3]
	v_mov_b32_e32 v1, v9
	v_add_u32_e32 v8, v2, v8
	v_add_u32_e32 v2, 0x1000, v2
	v_add_u32_e32 v3, 0x800, v3
	v_mov_b32_e32 v46, v8
	v_ashrrev_i32_e32 v6, 31, v1
	v_lshrrev_b32_e32 v6, 28, v6
	v_add_u32_e32 v8, v1, v6
	v_mov_b64_e32 v[4:5], s[70:71]
	v_ashrrev_i32_e32 v6, 4, v8
	v_mad_i64_i32 v[4:5], s[12:13], v6, s74, v[4:5]
	v_lshlrev_b32_e32 v6, 7, v6
	v_sub_u32_e32 v6, v3, v6
	v_ashrrev_i32_e32 v7, 31, v6
	v_lshl_add_u64 v[4:5], v[6:7], 1, v[4:5]
	global_load_dwordx4 v[28:31], v[4:5], off offset:2048
	v_add_u32_e32 v9, 0x100, v1
	v_cmp_lt_i32_e32 vcc, s77, v1
	v_and_b32_e32 v8, -16, v8
	s_or_b64 s[2:3], vcc, s[2:3]
	v_mov_b32_e32 v1, v9
	v_add_u32_e32 v8, v2, v8
	v_add_u32_e32 v2, 0x1000, v2
	v_add_u32_e32 v3, 0x800, v3
	v_mov_b32_e32 v47, v8
	v_ashrrev_i32_e32 v6, 31, v1
	v_lshrrev_b32_e32 v6, 28, v6
	v_add_u32_e32 v8, v1, v6
	v_mov_b64_e32 v[4:5], s[70:71]
	v_ashrrev_i32_e32 v6, 4, v8
	v_mad_i64_i32 v[4:5], s[12:13], v6, s74, v[4:5]
	v_lshlrev_b32_e32 v6, 7, v6
	v_sub_u32_e32 v6, v3, v6
	v_ashrrev_i32_e32 v7, 31, v6
	v_lshl_add_u64 v[4:5], v[6:7], 1, v[4:5]
	global_load_dwordx4 v[32:35], v[4:5], off offset:2048
	v_add_u32_e32 v9, 0x100, v1
	v_cmp_lt_i32_e32 vcc, s77, v1
	v_and_b32_e32 v8, -16, v8
	s_or_b64 s[2:3], vcc, s[2:3]
	v_mov_b32_e32 v1, v9
	v_add_u32_e32 v8, v2, v8
	v_add_u32_e32 v2, 0x1000, v2
	v_add_u32_e32 v3, 0x800, v3
	v_mov_b32_e32 v48, v8
	v_ashrrev_i32_e32 v6, 31, v1
	v_lshrrev_b32_e32 v6, 28, v6
	v_add_u32_e32 v8, v1, v6
	v_mov_b64_e32 v[4:5], s[70:71]
	v_ashrrev_i32_e32 v6, 4, v8
	v_mad_i64_i32 v[4:5], s[12:13], v6, s74, v[4:5]
	v_lshlrev_b32_e32 v6, 7, v6
	v_sub_u32_e32 v6, v3, v6
	v_ashrrev_i32_e32 v7, 31, v6
	v_lshl_add_u64 v[4:5], v[6:7], 1, v[4:5]
	global_load_dwordx4 v[36:39], v[4:5], off offset:2048
	v_add_u32_e32 v9, 0x100, v1
	v_cmp_lt_i32_e32 vcc, s77, v1
	v_and_b32_e32 v8, -16, v8
	s_or_b64 s[2:3], vcc, s[2:3]
	v_mov_b32_e32 v1, v9
	v_add_u32_e32 v8, v2, v8
	v_add_u32_e32 v2, 0x1000, v2
	v_add_u32_e32 v3, 0x800, v3
	v_mov_b32_e32 v49, v8
	v_ashrrev_i32_e32 v6, 31, v1
	v_lshrrev_b32_e32 v6, 28, v6
	v_add_u32_e32 v8, v1, v6
	v_mov_b64_e32 v[4:5], s[70:71]
	v_ashrrev_i32_e32 v6, 4, v8
	v_mad_i64_i32 v[4:5], s[12:13], v6, s74, v[4:5]
	v_lshlrev_b32_e32 v6, 7, v6
	v_sub_u32_e32 v6, v3, v6
	v_ashrrev_i32_e32 v7, 31, v6
	v_lshl_add_u64 v[4:5], v[6:7], 1, v[4:5]
	global_load_dwordx4 v[40:43], v[4:5], off offset:2048
	v_add_u32_e32 v9, 0x100, v1
	v_cmp_lt_i32_e32 vcc, s77, v1
	v_and_b32_e32 v8, -16, v8
	s_or_b64 s[2:3], vcc, s[2:3]
	v_mov_b32_e32 v1, v9
	v_add_u32_e32 v8, v2, v8
	v_add_u32_e32 v2, 0x1000, v2
	v_add_u32_e32 v3, 0x800, v3
	v_mov_b32_e32 v50, v8
	v_ashrrev_i32_e32 v6, 31, v1
	v_lshrrev_b32_e32 v6, 28, v6
	v_add_u32_e32 v8, v1, v6
	v_mov_b64_e32 v[4:5], s[70:71]
	v_ashrrev_i32_e32 v6, 4, v8
	v_mad_i64_i32 v[4:5], s[12:13], v6, s74, v[4:5]
	v_lshlrev_b32_e32 v6, 7, v6
	v_sub_u32_e32 v6, v3, v6
	v_ashrrev_i32_e32 v7, 31, v6
	v_lshl_add_u64 v[4:5], v[6:7], 1, v[4:5]
	global_load_dwordx4 v[4:7], v[4:5], off offset:2048
	v_add_u32_e32 v9, 0x100, v1
	v_cmp_lt_i32_e32 vcc, s77, v1
	v_and_b32_e32 v8, -16, v8
	s_or_b64 s[2:3], vcc, s[2:3]
	v_mov_b32_e32 v1, v9
	v_add_u32_e32 v8, v2, v8
	v_add_u32_e32 v2, 0x1000, v2
	v_add_u32_e32 v3, 0x800, v3
	s_waitcnt vmcnt(7)
	ds_write_b128 v44, v[16:19]
	s_waitcnt vmcnt(6)
	ds_write_b128 v45, v[20:23]
	s_waitcnt vmcnt(5)
	ds_write_b128 v46, v[24:27]
	s_waitcnt vmcnt(4)
	ds_write_b128 v47, v[28:31]
	s_waitcnt vmcnt(3)
	ds_write_b128 v48, v[32:35]
	s_waitcnt vmcnt(2)
	ds_write_b128 v49, v[36:39]
	s_waitcnt vmcnt(1)
	ds_write_b128 v50, v[40:43]
	s_waitcnt vmcnt(0)
	ds_write_b128 v8, v[4:7]

.LBB0_932:
	v_ashrrev_i32_e32 v3, 31, v0
	v_lshrrev_b32_e32 v3, 28, v3
	v_add_u32_e32 v3, v0, v3
	v_mov_b64_e32 v[4:5], s[70:71]
	v_ashrrev_i32_e32 v6, 4, v3
	v_mad_i64_i32 v[4:5], s[68:69], v6, s74, v[4:5]
	v_lshlrev_b32_e32 v6, 7, v6
	v_sub_u32_e32 v6, v2, v6
	v_ashrrev_i32_e32 v7, 31, v6
	v_lshl_add_u64 v[4:5], v[6:7], 1, v[4:5]
	global_load_dwordx4 v[16:19], v[4:5], off offset:3072
	v_add_u32_e32 v8, 0x100, v0
	v_cmp_lt_i32_e32 vcc, s77, v0
	v_and_b32_e32 v3, -16, v3
	s_or_b64 s[54:55], vcc, s[54:55]
	v_mov_b32_e32 v0, v8
	v_add_u32_e32 v3, v1, v3
	v_add_u32_e32 v1, 0x1000, v1
	v_add_u32_e32 v2, 0x800, v2
	v_mov_b32_e32 v44, v3
	v_ashrrev_i32_e32 v3, 31, v0
	v_lshrrev_b32_e32 v3, 28, v3
	v_add_u32_e32 v3, v0, v3
	v_mov_b64_e32 v[4:5], s[70:71]
	v_ashrrev_i32_e32 v6, 4, v3
	v_mad_i64_i32 v[4:5], s[68:69], v6, s74, v[4:5]
	v_lshlrev_b32_e32 v6, 7, v6
	v_sub_u32_e32 v6, v2, v6
	v_ashrrev_i32_e32 v7, 31, v6
	v_lshl_add_u64 v[4:5], v[6:7], 1, v[4:5]
	global_load_dwordx4 v[20:23], v[4:5], off offset:3072
	v_add_u32_e32 v8, 0x100, v0
	v_cmp_lt_i32_e32 vcc, s77, v0
	v_and_b32_e32 v3, -16, v3
	s_or_b64 s[54:55], vcc, s[54:55]
	v_mov_b32_e32 v0, v8
	v_add_u32_e32 v3, v1, v3
	v_add_u32_e32 v1, 0x1000, v1
	v_add_u32_e32 v2, 0x800, v2
	v_mov_b32_e32 v45, v3
	v_ashrrev_i32_e32 v3, 31, v0
	v_lshrrev_b32_e32 v3, 28, v3
	v_add_u32_e32 v3, v0, v3
	v_mov_b64_e32 v[4:5], s[70:71]
	v_ashrrev_i32_e32 v6, 4, v3
	v_mad_i64_i32 v[4:5], s[68:69], v6, s74, v[4:5]
	v_lshlrev_b32_e32 v6, 7, v6
	v_sub_u32_e32 v6, v2, v6
	v_ashrrev_i32_e32 v7, 31, v6
	v_lshl_add_u64 v[4:5], v[6:7], 1, v[4:5]
	global_load_dwordx4 v[24:27], v[4:5], off offset:3072
	v_add_u32_e32 v8, 0x100, v0
	v_cmp_lt_i32_e32 vcc, s77, v0
	v_and_b32_e32 v3, -16, v3
	s_or_b64 s[54:55], vcc, s[54:55]
	v_mov_b32_e32 v0, v8
	v_add_u32_e32 v3, v1, v3
	v_add_u32_e32 v1, 0x1000, v1
	v_add_u32_e32 v2, 0x800, v2
	v_mov_b32_e32 v46, v3
	v_ashrrev_i32_e32 v3, 31, v0
	v_lshrrev_b32_e32 v3, 28, v3
	v_add_u32_e32 v3, v0, v3
	v_mov_b64_e32 v[4:5], s[70:71]
	v_ashrrev_i32_e32 v6, 4, v3
	v_mad_i64_i32 v[4:5], s[68:69], v6, s74, v[4:5]
	v_lshlrev_b32_e32 v6, 7, v6
	v_sub_u32_e32 v6, v2, v6
	v_ashrrev_i32_e32 v7, 31, v6
	v_lshl_add_u64 v[4:5], v[6:7], 1, v[4:5]
	global_load_dwordx4 v[28:31], v[4:5], off offset:3072
	v_add_u32_e32 v8, 0x100, v0
	v_cmp_lt_i32_e32 vcc, s77, v0
	v_and_b32_e32 v3, -16, v3
	s_or_b64 s[54:55], vcc, s[54:55]
	v_mov_b32_e32 v0, v8
	v_add_u32_e32 v3, v1, v3
	v_add_u32_e32 v1, 0x1000, v1
	v_add_u32_e32 v2, 0x800, v2
	v_mov_b32_e32 v47, v3
	v_ashrrev_i32_e32 v3, 31, v0
	v_lshrrev_b32_e32 v3, 28, v3
	v_add_u32_e32 v3, v0, v3
	v_mov_b64_e32 v[4:5], s[70:71]
	v_ashrrev_i32_e32 v6, 4, v3
	v_mad_i64_i32 v[4:5], s[68:69], v6, s74, v[4:5]
	v_lshlrev_b32_e32 v6, 7, v6
	v_sub_u32_e32 v6, v2, v6
	v_ashrrev_i32_e32 v7, 31, v6
	v_lshl_add_u64 v[4:5], v[6:7], 1, v[4:5]
	global_load_dwordx4 v[32:35], v[4:5], off offset:3072
	v_add_u32_e32 v8, 0x100, v0
	v_cmp_lt_i32_e32 vcc, s77, v0
	v_and_b32_e32 v3, -16, v3
	s_or_b64 s[54:55], vcc, s[54:55]
	v_mov_b32_e32 v0, v8
	v_add_u32_e32 v3, v1, v3
	v_add_u32_e32 v1, 0x1000, v1
	v_add_u32_e32 v2, 0x800, v2
	v_mov_b32_e32 v48, v3
	v_ashrrev_i32_e32 v3, 31, v0
	v_lshrrev_b32_e32 v3, 28, v3
	v_add_u32_e32 v3, v0, v3
	v_mov_b64_e32 v[4:5], s[70:71]
	v_ashrrev_i32_e32 v6, 4, v3
	v_mad_i64_i32 v[4:5], s[68:69], v6, s74, v[4:5]
	v_lshlrev_b32_e32 v6, 7, v6
	v_sub_u32_e32 v6, v2, v6
	v_ashrrev_i32_e32 v7, 31, v6
	v_lshl_add_u64 v[4:5], v[6:7], 1, v[4:5]
	global_load_dwordx4 v[36:39], v[4:5], off offset:3072
	v_add_u32_e32 v8, 0x100, v0
	v_cmp_lt_i32_e32 vcc, s77, v0
	v_and_b32_e32 v3, -16, v3
	s_or_b64 s[54:55], vcc, s[54:55]
	v_mov_b32_e32 v0, v8
	v_add_u32_e32 v3, v1, v3
	v_add_u32_e32 v1, 0x1000, v1
	v_add_u32_e32 v2, 0x800, v2
	v_mov_b32_e32 v49, v3
	v_ashrrev_i32_e32 v3, 31, v0
	v_lshrrev_b32_e32 v3, 28, v3
	v_add_u32_e32 v3, v0, v3
	v_mov_b64_e32 v[4:5], s[70:71]
	v_ashrrev_i32_e32 v6, 4, v3
	v_mad_i64_i32 v[4:5], s[68:69], v6, s74, v[4:5]
	v_lshlrev_b32_e32 v6, 7, v6
	v_sub_u32_e32 v6, v2, v6
	v_ashrrev_i32_e32 v7, 31, v6
	v_lshl_add_u64 v[4:5], v[6:7], 1, v[4:5]
	global_load_dwordx4 v[40:43], v[4:5], off offset:3072
	v_add_u32_e32 v8, 0x100, v0
	v_cmp_lt_i32_e32 vcc, s77, v0
	v_and_b32_e32 v3, -16, v3
	s_or_b64 s[54:55], vcc, s[54:55]
	v_mov_b32_e32 v0, v8
	v_add_u32_e32 v3, v1, v3
	v_add_u32_e32 v1, 0x1000, v1
	v_add_u32_e32 v2, 0x800, v2
	v_mov_b32_e32 v50, v3
	v_ashrrev_i32_e32 v3, 31, v0
	v_lshrrev_b32_e32 v3, 28, v3
	v_add_u32_e32 v3, v0, v3
	v_mov_b64_e32 v[4:5], s[70:71]
	v_ashrrev_i32_e32 v6, 4, v3
	v_mad_i64_i32 v[4:5], s[68:69], v6, s74, v[4:5]
	v_lshlrev_b32_e32 v6, 7, v6
	v_sub_u32_e32 v6, v2, v6
	v_ashrrev_i32_e32 v7, 31, v6
	v_lshl_add_u64 v[4:5], v[6:7], 1, v[4:5]
	global_load_dwordx4 v[4:7], v[4:5], off offset:3072
	v_add_u32_e32 v8, 0x100, v0
	v_cmp_lt_i32_e32 vcc, s77, v0
	v_and_b32_e32 v3, -16, v3
	s_or_b64 s[54:55], vcc, s[54:55]
	v_mov_b32_e32 v0, v8
	v_add_u32_e32 v3, v1, v3
	v_add_u32_e32 v1, 0x1000, v1
	v_add_u32_e32 v2, 0x800, v2
	s_waitcnt vmcnt(7)
	ds_write_b128 v44, v[16:19]
	s_waitcnt vmcnt(6)
	ds_write_b128 v45, v[20:23]
	s_waitcnt vmcnt(5)
	ds_write_b128 v46, v[24:27]
	s_waitcnt vmcnt(4)
	ds_write_b128 v47, v[28:31]
	s_waitcnt vmcnt(3)
	ds_write_b128 v48, v[32:35]
	s_waitcnt vmcnt(2)
	ds_write_b128 v49, v[36:39]
	s_waitcnt vmcnt(1)
	ds_write_b128 v50, v[40:43]
	s_waitcnt vmcnt(0)
	ds_write_b128 v3, v[4:7]

.LBB0_1101:
	s_waitcnt lgkmcnt(0)
	v_ashrrev_i32_e32 v3, 31, v0
	v_lshrrev_b32_e32 v3, 28, v3
	v_add_u32_e32 v3, v0, v3
	v_ashrrev_i32_e32 v4, 4, v3
	v_ashrrev_i32_e32 v5, 31, v4
	v_lshlrev_b32_e32 v6, 7, v4
	v_lshlrev_b64 v[4:5], 8, v[4:5]
	v_sub_u32_e32 v6, v2, v6
	v_lshl_add_u64 v[4:5], s[6:7], 0, v[4:5]
	v_ashrrev_i32_e32 v7, 31, v6
	v_lshl_add_u64 v[4:5], v[6:7], 1, v[4:5]
	global_load_dwordx4 v[16:19], v[4:5], off
	v_add_u32_e32 v8, 0x100, v0
	v_cmp_lt_i32_e32 vcc, s77, v0
	v_and_b32_e32 v3, -16, v3
	s_or_b64 s[12:13], vcc, s[12:13]
	v_mov_b32_e32 v0, v8
	v_add_u32_e32 v3, v1, v3
	v_add_u32_e32 v1, 0x1000, v1
	v_add_u32_e32 v2, 0x800, v2
	v_mov_b32_e32 v44, v3
	s_waitcnt lgkmcnt(0)
	v_ashrrev_i32_e32 v3, 31, v0
	v_lshrrev_b32_e32 v3, 28, v3
	v_add_u32_e32 v3, v0, v3
	v_ashrrev_i32_e32 v4, 4, v3
	v_ashrrev_i32_e32 v5, 31, v4
	v_lshlrev_b32_e32 v6, 7, v4
	v_lshlrev_b64 v[4:5], 8, v[4:5]
	v_sub_u32_e32 v6, v2, v6
	v_lshl_add_u64 v[4:5], s[6:7], 0, v[4:5]
	v_ashrrev_i32_e32 v7, 31, v6
	v_lshl_add_u64 v[4:5], v[6:7], 1, v[4:5]
	global_load_dwordx4 v[20:23], v[4:5], off
	v_add_u32_e32 v8, 0x100, v0
	v_cmp_lt_i32_e32 vcc, s77, v0
	v_and_b32_e32 v3, -16, v3
	s_or_b64 s[12:13], vcc, s[12:13]
	v_mov_b32_e32 v0, v8
	v_add_u32_e32 v3, v1, v3
	v_add_u32_e32 v1, 0x1000, v1
	v_add_u32_e32 v2, 0x800, v2
	v_mov_b32_e32 v45, v3
	s_waitcnt lgkmcnt(0)
	v_ashrrev_i32_e32 v3, 31, v0
	v_lshrrev_b32_e32 v3, 28, v3
	v_add_u32_e32 v3, v0, v3
	v_ashrrev_i32_e32 v4, 4, v3
	v_ashrrev_i32_e32 v5, 31, v4
	v_lshlrev_b32_e32 v6, 7, v4
	v_lshlrev_b64 v[4:5], 8, v[4:5]
	v_sub_u32_e32 v6, v2, v6
	v_lshl_add_u64 v[4:5], s[6:7], 0, v[4:5]
	v_ashrrev_i32_e32 v7, 31, v6
	v_lshl_add_u64 v[4:5], v[6:7], 1, v[4:5]
	global_load_dwordx4 v[24:27], v[4:5], off
	v_add_u32_e32 v8, 0x100, v0
	v_cmp_lt_i32_e32 vcc, s77, v0
	v_and_b32_e32 v3, -16, v3
	s_or_b64 s[12:13], vcc, s[12:13]
	v_mov_b32_e32 v0, v8
	v_add_u32_e32 v3, v1, v3
	v_add_u32_e32 v1, 0x1000, v1
	v_add_u32_e32 v2, 0x800, v2
	v_mov_b32_e32 v46, v3
	s_waitcnt lgkmcnt(0)
	v_ashrrev_i32_e32 v3, 31, v0
	v_lshrrev_b32_e32 v3, 28, v3
	v_add_u32_e32 v3, v0, v3
	v_ashrrev_i32_e32 v4, 4, v3
	v_ashrrev_i32_e32 v5, 31, v4
	v_lshlrev_b32_e32 v6, 7, v4
	v_lshlrev_b64 v[4:5], 8, v[4:5]
	v_sub_u32_e32 v6, v2, v6
	v_lshl_add_u64 v[4:5], s[6:7], 0, v[4:5]
	v_ashrrev_i32_e32 v7, 31, v6
	v_lshl_add_u64 v[4:5], v[6:7], 1, v[4:5]
	global_load_dwordx4 v[28:31], v[4:5], off
	v_add_u32_e32 v8, 0x100, v0
	v_cmp_lt_i32_e32 vcc, s77, v0
	v_and_b32_e32 v3, -16, v3
	s_or_b64 s[12:13], vcc, s[12:13]
	v_mov_b32_e32 v0, v8
	v_add_u32_e32 v3, v1, v3
	v_add_u32_e32 v1, 0x1000, v1
	v_add_u32_e32 v2, 0x800, v2
	v_mov_b32_e32 v47, v3
	s_waitcnt lgkmcnt(0)
	v_ashrrev_i32_e32 v3, 31, v0
	v_lshrrev_b32_e32 v3, 28, v3
	v_add_u32_e32 v3, v0, v3
	v_ashrrev_i32_e32 v4, 4, v3
	v_ashrrev_i32_e32 v5, 31, v4
	v_lshlrev_b32_e32 v6, 7, v4
	v_lshlrev_b64 v[4:5], 8, v[4:5]
	v_sub_u32_e32 v6, v2, v6
	v_lshl_add_u64 v[4:5], s[6:7], 0, v[4:5]
	v_ashrrev_i32_e32 v7, 31, v6
	v_lshl_add_u64 v[4:5], v[6:7], 1, v[4:5]
	global_load_dwordx4 v[32:35], v[4:5], off
	v_add_u32_e32 v8, 0x100, v0
	v_cmp_lt_i32_e32 vcc, s77, v0
	v_and_b32_e32 v3, -16, v3
	s_or_b64 s[12:13], vcc, s[12:13]
	v_mov_b32_e32 v0, v8
	v_add_u32_e32 v3, v1, v3
	v_add_u32_e32 v1, 0x1000, v1
	v_add_u32_e32 v2, 0x800, v2
	v_mov_b32_e32 v48, v3
	s_waitcnt lgkmcnt(0)
	v_ashrrev_i32_e32 v3, 31, v0
	v_lshrrev_b32_e32 v3, 28, v3
	v_add_u32_e32 v3, v0, v3
	v_ashrrev_i32_e32 v4, 4, v3
	v_ashrrev_i32_e32 v5, 31, v4
	v_lshlrev_b32_e32 v6, 7, v4
	v_lshlrev_b64 v[4:5], 8, v[4:5]
	v_sub_u32_e32 v6, v2, v6
	v_lshl_add_u64 v[4:5], s[6:7], 0, v[4:5]
	v_ashrrev_i32_e32 v7, 31, v6
	v_lshl_add_u64 v[4:5], v[6:7], 1, v[4:5]
	global_load_dwordx4 v[36:39], v[4:5], off
	v_add_u32_e32 v8, 0x100, v0
	v_cmp_lt_i32_e32 vcc, s77, v0
	v_and_b32_e32 v3, -16, v3
	s_or_b64 s[12:13], vcc, s[12:13]
	v_mov_b32_e32 v0, v8
	v_add_u32_e32 v3, v1, v3
	v_add_u32_e32 v1, 0x1000, v1
	v_add_u32_e32 v2, 0x800, v2
	v_mov_b32_e32 v49, v3
	s_waitcnt lgkmcnt(0)
	v_ashrrev_i32_e32 v3, 31, v0
	v_lshrrev_b32_e32 v3, 28, v3
	v_add_u32_e32 v3, v0, v3
	v_ashrrev_i32_e32 v4, 4, v3
	v_ashrrev_i32_e32 v5, 31, v4
	v_lshlrev_b32_e32 v6, 7, v4
	v_lshlrev_b64 v[4:5], 8, v[4:5]
	v_sub_u32_e32 v6, v2, v6
	v_lshl_add_u64 v[4:5], s[6:7], 0, v[4:5]
	v_ashrrev_i32_e32 v7, 31, v6
	v_lshl_add_u64 v[4:5], v[6:7], 1, v[4:5]
	global_load_dwordx4 v[40:43], v[4:5], off
	v_add_u32_e32 v8, 0x100, v0
	v_cmp_lt_i32_e32 vcc, s77, v0
	v_and_b32_e32 v3, -16, v3
	s_or_b64 s[12:13], vcc, s[12:13]
	v_mov_b32_e32 v0, v8
	v_add_u32_e32 v3, v1, v3
	v_add_u32_e32 v1, 0x1000, v1
	v_add_u32_e32 v2, 0x800, v2
	v_mov_b32_e32 v50, v3
	s_waitcnt lgkmcnt(0)
	v_ashrrev_i32_e32 v3, 31, v0
	v_lshrrev_b32_e32 v3, 28, v3
	v_add_u32_e32 v3, v0, v3
	v_ashrrev_i32_e32 v4, 4, v3
	v_ashrrev_i32_e32 v5, 31, v4
	v_lshlrev_b32_e32 v6, 7, v4
	v_lshlrev_b64 v[4:5], 8, v[4:5]
	v_sub_u32_e32 v6, v2, v6
	v_lshl_add_u64 v[4:5], s[6:7], 0, v[4:5]
	v_ashrrev_i32_e32 v7, 31, v6
	v_lshl_add_u64 v[4:5], v[6:7], 1, v[4:5]
	global_load_dwordx4 v[4:7], v[4:5], off
	v_add_u32_e32 v8, 0x100, v0
	v_cmp_lt_i32_e32 vcc, s77, v0
	v_and_b32_e32 v3, -16, v3
	s_or_b64 s[12:13], vcc, s[12:13]
	v_mov_b32_e32 v0, v8
	v_add_u32_e32 v3, v1, v3
	v_add_u32_e32 v1, 0x1000, v1
	v_add_u32_e32 v2, 0x800, v2
	s_waitcnt vmcnt(7)
	ds_write_b128 v44, v[16:19]
	s_waitcnt vmcnt(6)
	ds_write_b128 v45, v[20:23]
	s_waitcnt vmcnt(5)
	ds_write_b128 v46, v[24:27]
	s_waitcnt vmcnt(4)
	ds_write_b128 v47, v[28:31]
	s_waitcnt vmcnt(3)
	ds_write_b128 v48, v[32:35]
	s_waitcnt vmcnt(2)
	ds_write_b128 v49, v[36:39]
	s_waitcnt vmcnt(1)
	ds_write_b128 v50, v[40:43]
	s_waitcnt vmcnt(0)
	ds_write_b128 v3, v[4:7]
	s_or_b64 exec, exec, s[12:13]
